# stack: GEMM phase prologue issues K-tile-1 DMA loads before the first wait (two load round trips overlap); attention gain-max scan issues all 32 loads before one wait
# speedup vs baseline: 1.0001x; 1.0001x over previous
; #define PG8_STAGE(bufoff, gbase, voff) do { _Pragma("unroll") for (int _i = 0; _i < 2; ++_i) \
;         __builtin_amdgcn_global_load_lds((const unsigned*)((const char*)(gbase) + (voff)[_i]), (PG8_LAS unsigned*)(lds + (bufoff) + ldsw + _i * 8192), 16, 0, 0); } while (0)
; #define PG8_WAIT_V(n) asm volatile("s_waitcnt vmcnt(" #n ")" ::: "memory")
; #define PG8_BAR __builtin_amdgcn_s_barrier()
; template <class Epi, class Sched, bool ALIGN_EPI = false, bool SP2 = false>
; __device__ __forceinline__ void gemm_phase(PG8_LAS unsigned char* lds, const Gemm g, const Sched& S, const Epi& E, int wave_s) {
;     ...
;     if constexpr (SP2) {
;         PG8_STAGE(PG8_SB(0, 0), cB, voffB); PG8_STAGE(PG8_SB(0, 1), cB + hstepB, voffB); PG8_STAGE(PG8_SA(0, 0), cA, voffA); PG8_STAGE(PG8_SA(0, 1), cA + hstepA, voffA);
;         if (wr == 1) PG8_BAR;
;         PG8_WAIT_V(2); PG8_BAR;
;         PG8_STAGE(PG8_SB(1, 0), cB + kstep, voffB); PG8_STAGE(PG8_SA(1, 0), cA + kstep, voffA); PG8_STAGE(PG8_SB(1, 1), cB + hstepB + kstep, voffB);
;         PG8_WAIT_V(6); PG8_BAR;
.LBB0_302:
	s_add_u32 s10, s4, 0x14400000
	s_addc_u32 s11, s5, 0
	s_lshl_b32 s50, s92, 11
	s_lshl_b64 s[12:13], s[50:51], 2
	v_readlane_b32 s14, v255, 43
	s_waitcnt lgkmcnt(0)
	s_add_u32 s12, s6, s12
	v_readlane_b32 s15, v255, 44
	s_addc_u32 s13, s7, s13
	s_lshl_b64 s[14:15], s[14:15], 2
	s_add_u32 s4, s4, s14
	s_addc_u32 s5, s5, s15
	v_bfe_u32 v1, v10, 4, 2
	s_add_u32 s14, s4, 0x200000
	v_and_b32_e32 v228, 15, v10
	v_lshlrev_b32_e32 v17, 4, v1
	v_lshlrev_b32_e32 v10, 2, v10
	s_addc_u32 s15, s5, 0
	s_and_b32 s43, s20, 3
	s_lshl_b32 s44, s3, 6
	v_lshl_or_b32 v17, v228, 6, v17
	s_lshl_b32 s3, s3, 13
	v_and_b32_e32 v10, 32, v10
	s_add_i32 m0, s35, 0x18000
	v_lshl_add_u64 v[8:9], v[8:9], 0, s[60:61]
	v_bitop3_b32 v18, v17, s3, v10 bitop3:0xde
	s_lshl_b32 s45, s43, 5
	s_lshl_b32 s3, s43, 12
	global_load_lds_dwordx4 v[8:9], off
	v_lshl_add_u64 v[6:7], v[6:7], 0, s[60:61]
	s_add_i32 m0, s35, 0x1a000
	s_add_i32 s46, s35, 0x8000
	s_add_i32 s47, s35, 0xa000
	global_load_lds_dwordx4 v[6:7], off
	v_lshl_add_u64 v[2:3], v[2:3], 0, s[60:61]
	s_mov_b32 m0, s46
	s_add_u32 s4, s30, 0x20080
	global_load_lds_dwordx4 v[2:3], off
	v_lshl_add_u64 v[2:3], v[4:5], 0, s[60:61]
	s_mov_b32 m0, s47
	s_addc_u32 s5, s31, 0
	global_load_lds_dwordx4 v[2:3], off
	s_add_i32 m0, s35, 0x1c000
	v_lshl_add_u64 v[2:3], s[4:5], 0, v[214:215]
	global_load_lds_dwordx4 v[2:3], off
	v_lshl_add_u64 v[2:3], s[4:5], 0, v[210:211]
	s_add_i32 m0, s35, 0x1e000
	s_cmpk_lt_u32 s2, 0x100
	global_load_lds_dwordx4 v[2:3], off
	s_waitcnt vmcnt(8)
	s_barrier
	v_lshlrev_b32_e32 v2, 15, v15
	v_and_b32_e32 v2, 0xffff0000, v2
	v_lshl_add_u32 v2, v14, 12, v2
	v_and_b32_e32 v3, 1, v15
	v_lshl_or_b32 v2, v3, 6, v2
	v_lshl_add_u32 v218, v16, 1, v2
	v_lshlrev_b32_e32 v2, 15, v11
	v_and_b32_e32 v2, 0xffff0000, v2
	s_waitcnt vmcnt(6)
	v_lshl_add_u32 v2, v12, 12, v2
	v_and_b32_e32 v3, 1, v11
	v_bitop3_b32 v229, v17, s3, v10 bitop3:0xde
	s_cselect_b64 s[20:21], -1, 0
	s_cmp_lg_u64 s[6:7], 0
	v_lshl_or_b32 v2, v3, 6, v2
	v_readlane_b32 s2, v255, 21
	s_cselect_b64 s[26:27], -1, 0
	v_mov_b32_e32 v219, v0
	v_lshl_add_u32 v220, v13, 1, v2
	v_mov_b32_e32 v221, v0
	s_mov_b32 s77, 0
	v_add_u32_e32 v230, 0, v18
	v_readlane_b32 s50, v255, 11
	s_mov_b32 s80, s2
	s_barrier
	v_readlane_b32 s3, v255, 22
	s_branch .LBB0_305

; __device__ __forceinline__ float sum_x1(float s) { return s + DPP_MOVF(s, 0xB1); }
; #define PG8_LAS __attribute__((address_space(3)))
; #define PG8_STAGE(bufoff, gbase, voff) do { _Pragma("unroll") for (int _i = 0; _i < 2; ++_i) \
;         __builtin_amdgcn_global_load_lds((const unsigned*)((const char*)(gbase) + (voff)[_i]), (PG8_LAS unsigned*)(lds + (bufoff) + ldsw + _i * 8192), 16, 0, 0); } while (0)
; #define PG8_WAIT_V(n) asm volatile("s_waitcnt vmcnt(" #n ")" ::: "memory")
; #define PG8_BAR __builtin_amdgcn_s_barrier()
; __device__ __forceinline__ void prep_rstd(PG8_LAS unsigned char* lds, const float* ss, int tid, int pm) {
;     PG8_LAS float* RS = (PG8_LAS float*)(lds + LDS_RS_OFF);
;     const int row = tid >> 1, h = tid & 1; const f32x4* p = (const f32x4*)(ss + (size_t)(pm * BM + row) * 32 + 16 * h);
;     f32x4 a = p[0] + p[1]; const f32x4 b = p[2] + p[3]; a += b; float t = (a[0] + a[1]) + (a[2] + a[3]);
;     t = sum_x1(t);
;     if (h == 0) RS[row] = __builtin_amdgcn_rsqf(t * (1.0f / 2048.0f) + RMS_EPS);
; template <class Epi, class Sched, bool ALIGN_EPI = false, bool SP2 = false>
; __device__ __forceinline__ void gemm_phase(PG8_LAS unsigned char* lds, const Gemm g, const Sched& S, const Epi& E, int wave_s) {
;     ...
;     if constexpr (SP2) {
;         PG8_STAGE(PG8_SB(0, 0), cB, voffB); PG8_STAGE(PG8_SB(0, 1), cB + hstepB, voffB); PG8_STAGE(PG8_SA(0, 0), cA, voffA); PG8_STAGE(PG8_SA(0, 1), cA + hstepA, voffA);
;         if (wr == 1) PG8_BAR;
;         PG8_WAIT_V(2); PG8_BAR;
;         PG8_STAGE(PG8_SB(1, 0), cB + kstep, voffB); PG8_STAGE(PG8_SA(1, 0), cA + kstep, voffA); PG8_STAGE(PG8_SB(1, 1), cB + hstepB + kstep, voffB);
;         PG8_WAIT_V(6); PG8_BAR;
.LBB0_404:
	s_add_u32 s10, s4, 0x18400000
	s_addc_u32 s11, s5, 0
	s_lshl_b32 s3, s3, 5
	s_and_b32 s44, s3, 0x60
	s_add_i32 m0, s35, 0x18000
	v_lshl_add_u64 v[8:9], v[8:9], 0, s[60:61]
	s_lshl_b32 s43, s2, 6
	s_lshl_b32 s7, s2, 13
	s_lshl_b32 s3, s44, 7
	global_load_lds_dwordx4 v[8:9], off
	v_lshl_add_u64 v[6:7], v[6:7], 0, s[60:61]
	s_add_i32 m0, s35, 0x1a000
	s_add_i32 s45, s35, 0x8000
	s_add_i32 s46, s35, 0xa000
	global_load_lds_dwordx4 v[6:7], off
	v_lshl_add_u64 v[2:3], v[2:3], 0, s[60:61]
	s_mov_b32 m0, s45
	s_add_u32 s4, s30, 0x80080
	global_load_lds_dwordx4 v[2:3], off
	v_lshl_add_u64 v[2:3], v[4:5], 0, s[60:61]
	s_mov_b32 m0, s46
	s_addc_u32 s5, s31, 0
	global_load_lds_dwordx4 v[2:3], off
	s_add_i32 m0, s35, 0x1c000
	v_lshl_add_u64 v[2:3], s[4:5], 0, v[132:133]
	global_load_lds_dwordx4 v[2:3], off
	v_lshl_add_u64 v[2:3], s[4:5], 0, v[136:137]
	s_add_i32 m0, s35, 0x1e000
	v_bfe_u32 v146, v10, 4, 2
	global_load_lds_dwordx4 v[2:3], off
	s_waitcnt vmcnt(8)
	s_barrier
	v_and_b32_e32 v1, 15, v10
	v_lshlrev_b32_e32 v2, 4, v146
	v_lshlrev_b32_e32 v3, 2, v10
	v_lshl_or_b32 v2, v1, 6, v2
	v_and_b32_e32 v3, 32, v3
	v_bitop3_b32 v4, v2, s7, v3 bitop3:0xde
	v_bitop3_b32 v147, v2, s3, v3 bitop3:0xde
	v_lshlrev_b32_e32 v2, 15, v11
	v_and_b32_e32 v2, 0xffff0000, v2
	v_lshl_add_u32 v2, v12, 12, v2
	v_and_b32_e32 v3, 1, v11
	v_lshl_or_b32 v2, v3, 6, v2
	v_lshl_add_u32 v138, v13, 1, v2
	v_lshlrev_b32_e32 v2, 15, v14
	s_cmpk_lt_u32 s6, 0x100
	v_and_b32_e32 v2, 0xffff0000, v2
	s_waitcnt vmcnt(6)
	s_cselect_b64 s[12:13], -1, 0
	s_lshl_b32 s2, s2, 8
	v_lshl_add_u32 v2, v15, 12, v2
	v_and_b32_e32 v3, 1, v14
	s_add_i32 s90, s2, 0
	v_lshl_or_b32 v2, v3, 6, v2
	v_readlane_b32 s2, v255, 14
	s_add_i32 s47, s90, 0x22100
	s_add_i32 s50, s90, 0x22140
	s_add_i32 s77, s90, 0x22180
	s_add_i32 s80, s90, 0x221c0
	s_add_i32 s81, s90, 0x22300
	s_add_i32 s88, s90, 0x22340
	s_add_i32 s89, s90, 0x22380
	s_add_i32 s90, s90, 0x223c0
	v_mov_b32_e32 v139, v0
	v_lshl_add_u32 v140, v16, 1, v2
	v_mov_b32_e32 v141, v0
	s_mov_b32 s91, 0
	v_add_u32_e32 v148, 0, v4
	v_readlane_b32 s84, v255, 12
	s_mov_b32 s85, s2
	s_barrier
	v_readlane_b32 s3, v255, 15
	s_branch .LBB0_407

; #define LAS __attribute__((address_space(3)))
; __device__ __forceinline__ void attn_phase(int wave_s, LAS unsigned char* lds, const bf16* QKV, bf16* O, const float* qg, const float* kg, const float* sinks, const float* bt) {
;     ...
;     float gq = 0.f, gk = 0.f;
;     for (int d = 0; d < HD; ++d) { gq = fmaxf(gq, fabsf(qg[d])); gk = fmaxf(gk, fabsf(kg[d])); }
;     const float shift = 8.0f * gq * gk;
;     ...
;         const int h = kvh * 8 + wid; const float sink2 = (sinks[h] - shift) * LOG2E;
;         const LAS float* Bh = Bs + wid * 192 + (r32 - 4 * hi);
;         LAS float* wsf = (LAS float*)(lds + ALDS_END) + wid * 32;
;         const bf16* Qb = QKV + ((size_t)b * SEQ + nb * 128 + r32) * NQKV + h * HD + hi * 8;
;         v4u qw[4];
; #pragma unroll
;         for (int d0 = 0; d0 < 4; ++d0) qw[d0] = *(const v4u*)(Qb + d0 * 16);
.LBB0_472:
	global_load_dwordx4 v[128:131], v0, s[12:13]
	global_load_dwordx4 v[132:135], v0, s[12:13] offset:16
	global_load_dwordx4 v[136:139], v0, s[12:13] offset:32
	global_load_dwordx4 v[140:143], v0, s[12:13] offset:48
	global_load_dwordx4 v[144:147], v0, s[12:13] offset:64
	global_load_dwordx4 v[148:151], v0, s[12:13] offset:80
	global_load_dwordx4 v[152:155], v0, s[12:13] offset:96
	global_load_dwordx4 v[156:159], v0, s[12:13] offset:112
	global_load_dwordx4 v[160:163], v0, s[12:13] offset:128
	global_load_dwordx4 v[164:167], v0, s[12:13] offset:144
	global_load_dwordx4 v[168:171], v0, s[12:13] offset:160
	global_load_dwordx4 v[172:175], v0, s[12:13] offset:176
	global_load_dwordx4 v[176:179], v0, s[12:13] offset:192
	global_load_dwordx4 v[180:183], v0, s[12:13] offset:208
	global_load_dwordx4 v[184:187], v0, s[12:13] offset:224
	global_load_dwordx4 v[188:191], v0, s[12:13] offset:240
	global_load_dwordx4 v[4:7], v0, s[14:15]
	global_load_dwordx4 v[8:11], v0, s[14:15] offset:16
	global_load_dwordx4 v[12:15], v0, s[14:15] offset:32
	global_load_dwordx4 v[16:19], v0, s[14:15] offset:48
	global_load_dwordx4 v[192:195], v0, s[14:15] offset:64
	global_load_dwordx4 v[196:199], v0, s[14:15] offset:80
	global_load_dwordx4 v[200:203], v0, s[14:15] offset:96
	global_load_dwordx4 v[204:207], v0, s[14:15] offset:112
	global_load_dwordx4 v[208:211], v0, s[14:15] offset:128
	global_load_dwordx4 v[212:215], v0, s[14:15] offset:144
	global_load_dwordx4 v[216:219], v0, s[14:15] offset:160
	global_load_dwordx4 v[220:223], v0, s[14:15] offset:176
	global_load_dwordx4 v[224:227], v0, s[14:15] offset:192
	global_load_dwordx4 v[228:231], v0, s[14:15] offset:208
	global_load_dwordx4 v[92:95], v0, s[14:15] offset:224
	global_load_dwordx4 v[96:99], v0, s[14:15] offset:240
	s_waitcnt vmcnt(0)
	v_max3_f32 v3, v3, |v128|, |v129|
	v_max3_f32 v3, v3, |v130|, |v131|
	v_max3_f32 v3, v3, |v132|, |v133|
	v_max3_f32 v3, v3, |v134|, |v135|
	v_max3_f32 v3, v3, |v136|, |v137|
	v_max3_f32 v3, v3, |v138|, |v139|
	v_max3_f32 v3, v3, |v140|, |v141|
	v_max3_f32 v3, v3, |v142|, |v143|
	v_max3_f32 v3, v3, |v144|, |v145|
	v_max3_f32 v3, v3, |v146|, |v147|
	v_max3_f32 v3, v3, |v148|, |v149|
	v_max3_f32 v3, v3, |v150|, |v151|
	v_max3_f32 v3, v3, |v152|, |v153|
	v_max3_f32 v3, v3, |v154|, |v155|
	v_max3_f32 v3, v3, |v156|, |v157|
	v_max3_f32 v3, v3, |v158|, |v159|
	v_max3_f32 v3, v3, |v160|, |v161|
	v_max3_f32 v3, v3, |v162|, |v163|
	v_max3_f32 v3, v3, |v164|, |v165|
	v_max3_f32 v3, v3, |v166|, |v167|
	v_max3_f32 v3, v3, |v168|, |v169|
	v_max3_f32 v3, v3, |v170|, |v171|
	v_max3_f32 v3, v3, |v172|, |v173|
	v_max3_f32 v3, v3, |v174|, |v175|
	v_max3_f32 v3, v3, |v176|, |v177|
	v_max3_f32 v3, v3, |v178|, |v179|
	v_max3_f32 v3, v3, |v180|, |v181|
	v_max3_f32 v3, v3, |v182|, |v183|
	v_max3_f32 v3, v3, |v184|, |v185|
	v_max3_f32 v3, v3, |v186|, |v187|
	v_max3_f32 v3, v3, |v188|, |v189|
	v_max3_f32 v3, v3, |v190|, |v191|
	v_max3_f32 v2, v2, |v4|, |v5|
	v_max3_f32 v2, v2, |v6|, |v7|
	v_max3_f32 v2, v2, |v8|, |v9|
	v_max3_f32 v2, v2, |v10|, |v11|
	v_max3_f32 v2, v2, |v12|, |v13|
	v_max3_f32 v2, v2, |v14|, |v15|
	v_max3_f32 v2, v2, |v16|, |v17|
	v_max3_f32 v2, v2, |v18|, |v19|
	v_max3_f32 v2, v2, |v192|, |v193|
	v_max3_f32 v2, v2, |v194|, |v195|
	v_max3_f32 v2, v2, |v196|, |v197|
	v_max3_f32 v2, v2, |v198|, |v199|
	v_max3_f32 v2, v2, |v200|, |v201|
	v_max3_f32 v2, v2, |v202|, |v203|
	v_max3_f32 v2, v2, |v204|, |v205|
	v_max3_f32 v2, v2, |v206|, |v207|
	v_max3_f32 v2, v2, |v208|, |v209|
	v_max3_f32 v2, v2, |v210|, |v211|
	v_max3_f32 v2, v2, |v212|, |v213|
	v_max3_f32 v2, v2, |v214|, |v215|
	v_max3_f32 v2, v2, |v216|, |v217|
	v_max3_f32 v2, v2, |v218|, |v219|
	v_max3_f32 v2, v2, |v220|, |v221|
	v_max3_f32 v2, v2, |v222|, |v223|
	v_max3_f32 v2, v2, |v224|, |v225|
	v_max3_f32 v2, v2, |v226|, |v227|
	v_max3_f32 v2, v2, |v228|, |v229|
	v_max3_f32 v2, v2, |v230|, |v231|
	v_max3_f32 v2, v2, |v92|, |v93|
	v_max3_f32 v2, v2, |v94|, |v95|
	v_max3_f32 v2, v2, |v96|, |v97|
	v_max3_f32 v2, v2, |v98|, |v99|
	v_readlane_b32 s10, v255, 3
	v_or_b32_e32 v142, s55, v1
	v_readlane_b32 s11, v255, 4
	s_andn2_b64 vcc, exec, s[10:11]
	v_readfirstlane_b32 s23, v142
	s_cbranch_vccnz .LBB0_534
	s_add_u32 s20, s8, 0x1200000
	s_addc_u32 s21, s9, 0
	s_ashr_i32 s16, s23, 6
	s_add_u32 s26, s8, 0x18400000
	s_addc_u32 s27, s9, 0
	s_lshl_b32 s50, s92, 6
	s_lshl_b64 s[10:11], s[50:51], 2
	s_add_u32 s4, s4, s10
	s_addc_u32 s5, s5, s11
	s_add_u32 s28, s6, s10
	s_addc_u32 s29, s7, s11
	s_lshl_b32 s50, s92, 5
	s_lshl_b64 s[6:7], s[50:51], 2
	s_add_u32 s17, s2, s6
	s_movk_i32 s2, 0x600
	v_mul_f32_e32 v3, 0x41000000, v3
	v_bfe_u32 v6, v1, 5, 1
	v_cmp_gt_i32_e64 s[14:15], s2, v142
	s_mul_i32 s2, s16, 0x300
	v_mul_f32_e32 v143, v2, v3
	s_addc_u32 s22, s3, s7
	v_and_b32_e32 v128, 31, v1
	s_add_i32 s2, s2, 0
	v_lshlrev_b32_e32 v2, 2, v6
	v_and_b32_e32 v4, 32, v1
	v_mov_b32_e32 v5, v0
	s_lshl_b32 s3, s16, 12
	s_add_i32 s2, s2, 0x11200
	v_sub_u32_e32 v2, v128, v2
	v_lshl_add_u64 v[130:131], s[4:5], 0, v[4:5]
	s_add_i32 s3, s3, 0
	v_lshlrev_b32_e32 v4, 4, v1
	v_lshl_add_u32 v145, v2, 2, s2
	s_lshl_b32 s2, s16, 7
	s_add_i32 s3, s3, 0x14000
	v_and_b32_e32 v4, 0x70, v4
	v_and_b32_e32 v3, 63, v1
	s_add_i32 s2, s2, 0
	v_add_u32_e32 v148, s3, v4
	v_lshrrev_b32_e32 v4, 1, v1
	s_add_i32 s2, s2, 0x12a00
	v_cmp_gt_u32_e64 s[4:5], 32, v3
	v_lshlrev_b32_e32 v3, 4, v6
	v_and_b32_e32 v4, 16, v4
	v_lshl_add_u32 v146, v128, 2, s2
	v_add_u32_e32 v147, s2, v3
	v_lshl_add_u32 v7, v128, 1, s3
	v_bfe_u32 v8, v1, 3, 3
	v_lshl_add_u64 v[4:5], s[8:9], 0, v[4:5]
	s_mov_b64 s[2:3], 0x18428040
	v_and_b32_e32 v1, 7, v1
	v_lshlrev_b32_e32 v149, 7, v8
	v_lshl_add_u64 v[132:133], v[4:5], 0, s[2:3]
	v_mul_u32_u24_e32 v4, 0x90, v128
	v_lshlrev_b32_e32 v1, 4, v1
	v_lshlrev_b32_e32 v2, 3, v6
	v_mul_u32_u24_e32 v9, 0x208, v128
	v_lshlrev_b32_e32 v6, 9, v6
	v_or_b32_e32 v10, 0x400, v149
	v_or_b32_e32 v11, 0x800, v149
	v_or_b32_e32 v12, 0xc00, v149
	v_add3_u32 v150, v4, v3, 0
	s_add_i32 s2, 0, 0x9000
	v_lshl_or_b32 v4, v8, 12, v1
	v_mov_b32_e32 v5, v0
	v_readlane_b32 s35, v255, 0
	v_mul_f32_e32 v144, 0x3fb8aa3b, v143
	v_mov_b32_e32 v129, v0
	s_andn2_b32 s23, s23, 63
	v_add3_u32 v151, v9, v2, s2
	v_lshl_add_u64 v[134:135], s[8:9], 0, v[4:5]
	v_lshlrev_b32_e32 v136, 1, v2
	v_add_u32_e32 v152, v7, v6
	v_add_u32_e32 v153, v148, v10
	v_add_u32_e32 v154, v148, v11
	v_add_u32_e32 v155, v148, v12
	s_mov_b32 s34, s35
	global_load_dwordx4 v[164:167], v[130:131], off offset:16
	global_load_dwordx4 v[168:171], v[130:131], off
	global_load_dwordx4 v[172:175], v[130:131], off offset:80
	global_load_dwordx4 v[176:179], v[130:131], off offset:64
	global_load_dwordx4 v[180:183], v[130:131], off offset:144
	global_load_dwordx4 v[184:187], v[130:131], off offset:128
	global_load_dwordx4 v[188:191], v[130:131], off offset:208
	global_load_dwordx4 v[192:195], v[130:131], off offset:192
	s_branch .LBB0_476

; #define PG8_STAGE(bufoff, gbase, voff) do { _Pragma("unroll") for (int _i = 0; _i < 2; ++_i) \
;         __builtin_amdgcn_global_load_lds((const unsigned*)((const char*)(gbase) + (voff)[_i]), (PG8_LAS unsigned*)(lds + (bufoff) + ldsw + _i * 8192), 16, 0, 0); } while (0)
; #define PG8_WAIT_V(n) asm volatile("s_waitcnt vmcnt(" #n ")" ::: "memory")
; #define PG8_BAR __builtin_amdgcn_s_barrier()
; template <class Epi, class Sched, bool ALIGN_EPI = false, bool SP2 = false>
; __device__ __forceinline__ void gemm_phase(PG8_LAS unsigned char* lds, const Gemm g, const Sched& S, const Epi& E, int wave_s) {
;     ...
;     if constexpr (SP2) {
;         PG8_STAGE(PG8_SB(0, 0), cB, voffB); PG8_STAGE(PG8_SB(0, 1), cB + hstepB, voffB); PG8_STAGE(PG8_SA(0, 0), cA, voffA); PG8_STAGE(PG8_SA(0, 1), cA + hstepA, voffA);
;         if (wr == 1) PG8_BAR;
;         PG8_WAIT_V(2); PG8_BAR;
;         PG8_STAGE(PG8_SB(1, 0), cB + kstep, voffB); PG8_STAGE(PG8_SA(1, 0), cA + kstep, voffA); PG8_STAGE(PG8_SB(1, 1), cB + hstepB + kstep, voffB);
;         PG8_WAIT_V(6); PG8_BAR;
.LBB0_590:
	v_readlane_b32 s12, v255, 43
	s_add_u32 s10, s4, 0x14400000
	v_readlane_b32 s13, v255, 44
	s_addc_u32 s11, s5, 0
	s_lshl_b64 s[12:13], s[12:13], 2
	s_add_u32 s4, s4, s12
	s_addc_u32 s5, s5, s13
	v_bfe_u32 v1, v15, 4, 2
	s_add_u32 s12, s4, 0x200000
	v_and_b32_e32 v206, 15, v15
	v_lshlrev_b32_e32 v17, 4, v1
	v_lshlrev_b32_e32 v15, 2, v15
	s_addc_u32 s13, s5, 0
	s_and_b32 s43, s3, 3
	s_lshl_b32 s44, s2, 6
	v_lshl_or_b32 v17, v206, 6, v17
	s_lshl_b32 s2, s2, 13
	v_and_b32_e32 v15, 32, v15
	s_add_i32 m0, s35, 0x18000
	v_lshl_add_u64 v[8:9], v[8:9], 0, s[60:61]
	v_bitop3_b32 v18, v17, s2, v15 bitop3:0xde
	s_lshl_b32 s45, s43, 5
	s_lshl_b32 s2, s43, 12
	global_load_lds_dwordx4 v[8:9], off
	v_lshl_add_u64 v[6:7], v[6:7], 0, s[60:61]
	s_add_i32 m0, s35, 0x1a000
	s_add_i32 s46, s35, 0x8000
	s_add_i32 s47, s35, 0xa000
	v_bitop3_b32 v207, v17, s2, v15 bitop3:0xde
	global_load_lds_dwordx4 v[6:7], off
	v_lshl_add_u64 v[2:3], v[2:3], 0, s[60:61]
	s_mov_b32 m0, s46
	s_add_u32 s2, s30, 0x80080
	global_load_lds_dwordx4 v[2:3], off
	v_lshl_add_u64 v[2:3], v[4:5], 0, s[60:61]
	s_mov_b32 m0, s47
	s_addc_u32 s3, s31, 0
	global_load_lds_dwordx4 v[2:3], off
	s_add_i32 m0, s35, 0x1c000
	v_lshl_add_u64 v[2:3], s[2:3], 0, v[194:195]
	global_load_lds_dwordx4 v[2:3], off
	v_lshl_add_u64 v[2:3], s[2:3], 0, v[190:191]
	s_add_i32 m0, s35, 0x1e000
	s_cmpk_lt_u32 s6, 0x100
	global_load_lds_dwordx4 v[2:3], off
	s_waitcnt vmcnt(8)
	s_barrier
	v_lshlrev_b32_e32 v2, 15, v14
	v_and_b32_e32 v2, 0xffff0000, v2
	v_lshl_add_u32 v2, v13, 12, v2
	v_and_b32_e32 v3, 1, v14
	v_lshl_or_b32 v2, v3, 6, v2
	v_lshl_add_u32 v198, v16, 1, v2
	v_lshlrev_b32_e32 v2, 15, v10
	v_and_b32_e32 v2, 0xffff0000, v2
	s_waitcnt vmcnt(6)
	v_lshl_add_u32 v2, v11, 12, v2
	v_and_b32_e32 v3, 1, v10
	v_lshl_or_b32 v2, v3, 6, v2
	v_readlane_b32 s2, v255, 21
	s_cselect_b64 s[14:15], -1, 0
	v_mov_b32_e32 v199, v0
	v_lshl_add_u32 v200, v12, 1, v2
	v_mov_b32_e32 v201, v0
	s_mov_b32 s77, 0
	v_add_u32_e32 v208, 0, v18
	v_readlane_b32 s50, v255, 11
	s_mov_b32 s80, s2
	s_barrier
	v_readlane_b32 s3, v255, 22
	s_branch .LBB0_593

; #define PG8_STAGE(bufoff, gbase, voff) do { _Pragma("unroll") for (int _i = 0; _i < 2; ++_i) \
;         __builtin_amdgcn_global_load_lds((const unsigned*)((const char*)(gbase) + (voff)[_i]), (PG8_LAS unsigned*)(lds + (bufoff) + ldsw + _i * 8192), 16, 0, 0); } while (0)
; #define PG8_WAIT_V(n) asm volatile("s_waitcnt vmcnt(" #n ")" ::: "memory")
; #define PG8_BAR __builtin_amdgcn_s_barrier()
; template <class Epi, class Sched, bool ALIGN_EPI = false, bool SP2 = false>
; __device__ __forceinline__ void gemm_phase(PG8_LAS unsigned char* lds, const Gemm g, const Sched& S, const Epi& E, int wave_s) {
;     ...
;     for (int i = 0; i < 2; ++i) { int R, C; stage_rc(tid * 16 + i * 8192, R, C); const int Rb = Epi::PERM ? ((R & ~31) + perm32(R & 31)) : R;
;         const int Ra = Epi::AROW8 ? (((R >> 6) * 16 + (R & 15)) * 8 + ((R >> 4) & 3)) : R;
;         voffA[i] = (unsigned)(Ra * g.lda + C) * 2u; voffB[i] = (unsigned)(Rb * g.ldb + C) * 2u; }
;     const size_t kstep = (size_t)(BK * 2);
;     const size_t hstepA = (size_t)(Epi::AROW8 ? 4 : HALF) * g.lda * 2, hstepB = (size_t)HALF * g.ldb * 2;
;     ...
;     if constexpr (SP2) {
;         PG8_STAGE(PG8_SB(0, 0), cB, voffB); PG8_STAGE(PG8_SB(0, 1), cB + hstepB, voffB); PG8_STAGE(PG8_SA(0, 0), cA, voffA); PG8_STAGE(PG8_SA(0, 1), cA + hstepA, voffA);
;         if (wr == 1) PG8_BAR;
;         PG8_WAIT_V(2); PG8_BAR;
;         PG8_STAGE(PG8_SB(1, 0), cB + kstep, voffB); PG8_STAGE(PG8_SA(1, 0), cA + kstep, voffA); PG8_STAGE(PG8_SB(1, 1), cB + hstepB + kstep, voffB);
;         PG8_WAIT_V(6); PG8_BAR;
.LBB0_683:
	s_add_u32 s92, s8, 0x21400000
	s_addc_u32 s93, s9, 0
	s_lshl_b64 s[26:27], s[12:13], 2
	s_add_u32 s96, s4, s26
	s_addc_u32 s97, s5, s27
	s_lshl_b64 s[4:5], s[10:11], 2
	s_add_u32 s44, s6, s4
	s_addc_u32 s45, s7, s5
	v_and_b32_e32 v1, 15, v10
	s_add_u32 s46, s8, 0x2c400000
	v_bfe_u32 v253, v10, 4, 2
	v_lshlrev_b32_e32 v19, 6, v1
	v_lshlrev_b32_e32 v10, 2, v10
	s_addc_u32 s47, s9, 0
	s_and_b32 s4, s2, 3
	v_lshl_or_b32 v19, v253, 4, v19
	s_lshl_b32 s2, s34, 13
	v_and_b32_e32 v10, 32, v10
	s_add_i32 m0, s36, 0x18000
	v_lshl_add_u64 v[8:9], v[8:9], 0, s[60:61]
	v_bitop3_b32 v20, v19, s2, v10 bitop3:0xde
	s_lshl_b32 s50, s4, 5
	s_lshl_b32 s2, s4, 12
	global_load_lds_dwordx4 v[8:9], off
	v_lshl_add_u64 v[6:7], v[6:7], 0, s[60:61]
	s_add_i32 m0, s36, 0x1a000
	s_add_i32 s77, s36, 0x8000
	s_add_i32 s94, s36, 0xa000
	v_bitop3_b32 v251, v19, s2, v10 bitop3:0xde
	global_load_lds_dwordx4 v[6:7], off
	v_lshl_add_u64 v[2:3], v[2:3], 0, s[60:61]
	s_mov_b32 m0, s77
	s_add_u32 s2, s40, 0x80080
	global_load_lds_dwordx4 v[2:3], off
	v_lshl_add_u64 v[2:3], v[4:5], 0, s[60:61]
	s_mov_b32 m0, s94
	s_addc_u32 s3, s41, 0
	global_load_lds_dwordx4 v[2:3], off
	s_add_i32 m0, s36, 0x1c000
	v_lshl_add_u64 v[2:3], s[2:3], 0, v[238:239]
	global_load_lds_dwordx4 v[2:3], off
	v_lshl_add_u64 v[2:3], s[2:3], 0, v[242:243]
	s_add_i32 m0, s36, 0x1e000
	s_cmpk_lt_u32 s20, 0x100
	global_load_lds_dwordx4 v[2:3], off
	s_waitcnt vmcnt(8)
	s_barrier
	s_cselect_b64 s[26:27], -1, 0
	s_and_b32 s2, s20, 0xffffff00
	s_lshl_b32 s3, s4, 6
	s_or_b32 s95, s3, s2
	v_lshlrev_b32_e32 v2, 13, v12
	v_lshlrev_b32_e32 v3, 15, v14
	s_mov_b32 s2, 0xfff80000
	v_and_or_b32 v2, v2, s2, v3
	v_add3_u32 v3, v15, v11, v13
	v_lshl_add_u32 v2, v3, 1, v2
	v_mov_b32_e32 v3, v0
	s_mov_b64 s[4:5], 0x4080
	v_lshl_add_u64 v[244:245], v[2:3], 0, s[4:5]
	v_lshlrev_b32_e32 v2, 13, v16
	v_lshlrev_b32_e32 v3, 15, v17
	s_waitcnt vmcnt(6)
	v_and_or_b32 v2, v2, s2, v3
	v_add_u32_e32 v2, v2, v18
	v_mov_b32_e32 v3, v0
	v_readlane_b32 s2, v255, 32
	s_lshl_b32 s80, s34, 7
	v_lshl_add_u64 v[246:247], v[2:3], 0, s[4:5]
	s_mov_b32 s81, 0
	v_add_u32_e32 v252, 0, v20
	v_readlane_b32 s85, v255, 20
	s_mov_b32 s84, s2
	s_barrier
	v_readlane_b32 s3, v255, 33
	s_branch .LBB0_686

; #define PG8_STAGE(bufoff, gbase, voff) do { _Pragma("unroll") for (int _i = 0; _i < 2; ++_i) \
;         __builtin_amdgcn_global_load_lds((const unsigned*)((const char*)(gbase) + (voff)[_i]), (PG8_LAS unsigned*)(lds + (bufoff) + ldsw + _i * 8192), 16, 0, 0); } while (0)
; #define PG8_WAIT_V(n) asm volatile("s_waitcnt vmcnt(" #n ")" ::: "memory")
; #define PG8_BAR __builtin_amdgcn_s_barrier()
; template <class Epi, class Sched, bool ALIGN_EPI = false, bool SP2 = false>
; __device__ __forceinline__ void gemm_phase(PG8_LAS unsigned char* lds, const Gemm g, const Sched& S, const Epi& E, int wave_s) {
;     ...
;     for (int i = 0; i < 2; ++i) { int R, C; stage_rc(tid * 16 + i * 8192, R, C); const int Rb = Epi::PERM ? ((R & ~31) + perm32(R & 31)) : R;
;         const int Ra = Epi::AROW8 ? (((R >> 6) * 16 + (R & 15)) * 8 + ((R >> 4) & 3)) : R;
;         voffA[i] = (unsigned)(Ra * g.lda + C) * 2u; voffB[i] = (unsigned)(Rb * g.ldb + C) * 2u; }
;     const size_t kstep = (size_t)(BK * 2);
;     const size_t hstepA = (size_t)(Epi::AROW8 ? 4 : HALF) * g.lda * 2, hstepB = (size_t)HALF * g.ldb * 2;
;     ...
;     if constexpr (SP2) {
;         PG8_STAGE(PG8_SB(0, 0), cB, voffB); PG8_STAGE(PG8_SB(0, 1), cB + hstepB, voffB); PG8_STAGE(PG8_SA(0, 0), cA, voffA); PG8_STAGE(PG8_SA(0, 1), cA + hstepA, voffA);
;         if (wr == 1) PG8_BAR;
;         PG8_WAIT_V(2); PG8_BAR;
;         PG8_STAGE(PG8_SB(1, 0), cB + kstep, voffB); PG8_STAGE(PG8_SA(1, 0), cA + kstep, voffA); PG8_STAGE(PG8_SB(1, 1), cB + hstepB + kstep, voffB);
;         PG8_WAIT_V(6); PG8_BAR;
.LBB0_772:
	v_readlane_b32 s10, v255, 43
	v_readlane_b32 s11, v255, 44
	s_lshl_b64 s[10:11], s[10:11], 2
	s_add_u32 s5, s6, s10
	s_addc_u32 s10, s7, s11
	v_bfe_u32 v1, v18, 4, 2
	s_add_u32 s26, s5, 0x400000
	v_and_b32_e32 v210, 15, v18
	v_lshlrev_b32_e32 v19, 4, v1
	v_lshlrev_b32_e32 v18, 2, v18
	s_addc_u32 s27, s10, 0
	s_and_b32 s41, s4, 3
	s_lshl_b32 s42, s3, 6
	v_lshl_or_b32 v19, v210, 6, v19
	s_lshl_b32 s3, s3, 13
	v_and_b32_e32 v18, 32, v18
	v_bitop3_b32 v20, v19, s3, v18 bitop3:0xde
	s_lshl_b32 s43, s41, 5
	s_lshl_b32 s3, s41, 12
	s_add_u32 s28, s6, 0x14400000
	s_addc_u32 s29, s7, 0
	s_add_i32 m0, s35, 0x18000
	v_lshl_add_u64 v[8:9], v[8:9], 0, s[60:61]
	global_load_lds_dwordx4 v[8:9], off
	v_lshl_add_u64 v[6:7], v[6:7], 0, s[60:61]
	s_add_i32 m0, s35, 0x1a000
	s_add_i32 s44, s35, 0x8000
	s_add_i32 s45, s35, 0xa000
	global_load_lds_dwordx4 v[6:7], off
	v_lshl_add_u64 v[2:3], v[2:3], 0, s[60:61]
	s_mov_b32 m0, s44
	s_add_u32 s4, s30, 0x160080
	global_load_lds_dwordx4 v[2:3], off
	v_lshl_add_u64 v[2:3], v[4:5], 0, s[60:61]
	s_mov_b32 m0, s45
	s_addc_u32 s5, s31, 0
	global_load_lds_dwordx4 v[2:3], off
	s_add_i32 m0, s35, 0x1c000
	v_lshl_add_u64 v[2:3], s[4:5], 0, v[194:195]
	global_load_lds_dwordx4 v[2:3], off
	v_lshl_add_u64 v[2:3], s[4:5], 0, v[190:191]
	s_add_i32 m0, s35, 0x1e000
	s_movk_i32 s4, 0x1600
	global_load_lds_dwordx4 v[2:3], off
	s_waitcnt vmcnt(8)
	s_barrier
	v_lshrrev_b32_e32 v3, 1, v15
	v_mul_lo_u32 v2, v14, s4
	v_bitop3_b32 v211, v19, s3, v18 bitop3:0xde
	s_cmpk_lt_u32 s2, 0x100
	v_mad_u64_u32 v[2:3], s[2:3], v3, s50, v[2:3]
	v_or_b32_e32 v2, v2, v16
	v_add_lshl_u32 v2, v2, v17, 1
	v_mov_b32_e32 v3, v0
	s_mov_b64 s[6:7], 0x160080
	v_lshl_add_u64 v[198:199], v[2:3], 0, s[6:7]
	v_lshrrev_b32_e32 v3, 1, v10
	v_mul_lo_u32 v2, v11, s4
	v_mad_u64_u32 v[2:3], s[2:3], v3, s50, v[2:3]
	s_waitcnt vmcnt(6)
	s_cselect_b64 s[88:89], -1, 0
	s_waitcnt lgkmcnt(0)
	s_cmp_eq_u64 s[14:15], 0
	v_or_b32_e32 v2, v2, v12
	s_cselect_b64 s[90:91], -1, 0
	s_cmp_lg_u64 s[14:15], 0
	v_add_lshl_u32 v2, v2, v13, 1
	v_mov_b32_e32 v3, v0
	v_readlane_b32 s2, v255, 21
	s_cselect_b64 s[92:93], -1, 0
	v_lshl_add_u64 v[200:201], v[2:3], 0, s[6:7]
	s_mov_b32 s46, 0
	v_add_u32_e32 v212, 0, v20
	v_readlane_b32 s50, v255, 11
	s_mov_b32 s80, s2
	s_barrier
	v_readlane_b32 s3, v255, 22
	s_branch .LBB0_775
